# scan: all next-chunk loads and LDS commits moved to the four helper waves; worker waves only run the recurrence
# speedup vs baseline: 1.0086x; 1.0086x over previous
; #define otid() otid_(wid_k)
; DI void scan_block(float* ldsf, const u16* __restrict__ R, const u16* __restrict__ KP, const u16* __restrict__ KK, const u16* __restrict__ KKA,
;                    const u16* __restrict__ V, const float* __restrict__ Wd, float* __restrict__ Y, int blk, int wid_k) {
;   const int tid = otid(), lane = tid & 63, w = tid >> 6;
;   const int bh = blk >> 2, rq = blk & 3, b = bh >> 2, h = bh & 3;
;   const int ks = lane & 15, rowl = (w & 3) * 4 + (lane >> 4);
;   const bool worker = (w < 4);
;   float* ybuf = ldsf + 2 * 16 * 336;
;   float S0 = 0.f, S1 = 0.f, S2 = 0.f, S3 = 0.f, yreg = 0.f;
;   const size_t tb = (size_t)b * SEQ;
;   const int hc = h * 64;
;   const int a0i = tid >> 7, a0step = (tid & 127) >> 3, a0c = (tid & 7) * 8;
;   const int wstep = (tid & 255) >> 4, wc = (tid & 15) * 4;
;   const int vstep = (tid & 31) >> 1, vhalf = tid & 1;
;   uint4 p0, pv; float4 pw;
;   p0 = pv = make_uint4(0u, 0u, 0u, 0u); pw = make_float4(0.f, 0.f, 0.f, 0.f);
;     ...
;   __syncthreads();
;   SCAN_ISSUE(0);
;   SCAN_COMMIT(0);
;   __syncthreads();
.LBB0_1269:
	s_and_b64 vcc, exec, s[2:3]
	s_cbranch_vccz .LBB0_1314
	s_mov_b64 s[2:3], 0
	s_mov_b32 s2, s73
	s_mov_b64 s[48:49], s[42:43]
	s_mov_b32 s63, s33
	s_mov_b32 s2, s44
	v_mbcnt_lo_u32_b32 v0, -1, 0
	v_mbcnt_hi_u32_b32 v0, -1, v0
	s_setprio 3
	v_mbcnt_lo_u32_b32 v16, -1, 0
	v_mbcnt_hi_u32_b32 v16, -1, v16
	s_ashr_i32 s60, s63, 4
	v_or_b32_e32 v69, s97, v16
	v_ashrrev_i32_e32 v20, 7, v69
	v_lshlrev_b32_e32 v96, 1, v20
	v_subrev_u32_e32 v96, 3, v96
	v_lshlrev_b32_e32 v96, 23, v96
	v_add_u32_e32 v96, 0x2000, v96
	v_lshlrev_b32_e32 v0, 3, v16
	v_and_b32_e32 v22, 56, v0
	v_cmp_eq_u32_e32 vcc, 2, v20
	v_mov_b32_e32 v0, 0xe6a0000
	v_mov_b32_e32 v2, 0xeea0000
	s_ashr_i32 s61, s60, 31
	v_cndmask_b32_e32 v0, v0, v2, vcc
	v_cmp_ne_u32_e32 vcc, 1, v20
	v_mov_b32_e32 v2, 0xfea0000
	s_lshl_b64 s[8:9], s[60:61], 12
	v_bfe_u32 v17, v69, 3, 4
	v_cndmask_b32_e32 v0, v2, v0, vcc
	v_cmp_lt_u32_e32 vcc, s71, v69
	v_mov_b32_e32 v2, 0xf6a0000
	s_lshl_b32 s2, s63, 4
	v_cndmask_b32_e32 v0, v2, v0, vcc
	v_or_b32_e32 v4, s8, v17
	v_mov_b32_e32 v5, s9
	s_and_b32 s6, s2, 0xc0
	v_lshl_add_u64 v[2:3], s[48:49], 0, v[0:1]
	v_lshlrev_b64 v[4:5], 9, v[4:5]
	v_lshl_add_u64 v[2:3], v[2:3], 0, v[4:5]
	s_lshl_b32 s72, s6, 1
	v_lshl_add_u64 v[2:3], v[2:3], 0, s[72:73]
	v_lshlrev_b32_e32 v4, 1, v22
	v_mov_b32_e32 v5, v1
	v_lshl_add_u64 v[2:3], v[2:3], 0, v[4:5]
	s_barrier
	global_load_dwordx4 v[2:5], v[2:3], off
	v_and_b32_e32 v18, 15, v16
	v_lshlrev_b32_e32 v70, 2, v18
	s_movk_i32 s2, 0x100
	v_mov_b32_e32 v10, v1
	v_mov_b32_e32 v11, v1
	v_bfe_u32 v19, v69, 4, 4
	v_cmp_gt_i32_e64 s[2:3], s2, v69
	v_lshlrev_b32_e32 v54, 2, v70
	v_mov_b64_e32 v[6:7], v[10:11]
	v_mov_b64_e32 v[8:9], v[10:11]
	s_and_saveexec_b64 s[4:5], s[2:3]
	s_cbranch_execz .LBB0_1272
	v_or_b32_e32 v6, s8, v19
	v_mov_b32_e32 v7, s9
	v_lshlrev_b64 v[6:7], 10, v[6:7]
	v_lshl_add_u64 v[6:7], s[48:49], 0, v[6:7]
	s_lshl_b32 s6, s6, 2
	s_mov_b32 s7, s73
	v_lshl_add_u64 v[6:7], v[6:7], 0, s[6:7]
	v_mov_b32_e32 v55, v1
	v_lshl_add_u64 v[6:7], v[6:7], 0, v[54:55]
	v_add_co_u32_e32 v6, vcc, 0x10ea0000, v6
	s_nop 1
	v_addc_co_u32_e32 v7, vcc, 0, v7, vcc
	global_load_dwordx4 v[6:9], v[6:7], off

; DI void scan_block(float* ldsf, const u16* __restrict__ R, const u16* __restrict__ KP, const u16* __restrict__ KK, const u16* __restrict__ KKA,
;                    const u16* __restrict__ V, const float* __restrict__ Wd, float* __restrict__ Y, int blk, int wid_k) {
;     ...
;     if (c + 1 < SEQ / 16) SCAN_ISSUE(c + 1);
.LBB0_1282:
	s_cmpk_lg_i32 s62, 0xff
	s_cselect_b64 s[60:61], -1, 0
	s_cmpk_eq_i32 s62, 0xff
	s_cbranch_scc1 .LBB0_1288
	s_cmp_lt_u32 s97, 0x100
	s_cbranch_scc1 .LBB0_1288
	v_lshl_add_u64 v[2:3], s[48:49], 0, v[62:63]
	v_add_co_u32_e32 v94, vcc, v96, v2
	s_nop 1
	v_addc_co_u32_e32 v95, vcc, 0, v3, vcc
	v_add_co_u32_e32 v2, vcc, 0x2000, v2
	s_nop 1
	v_addc_co_u32_e32 v3, vcc, 0, v3, vcc
	global_load_dwordx4 v[2:5], v[2:3], off
	global_load_dwordx4 v[90:93], v[94:95], off
	v_lshl_add_u64 v[6:7], s[48:49], 0, v[60:61]
	v_add_co_u32_e32 v6, vcc, 0x10ea4000, v6
	s_nop 1
	v_addc_co_u32_e32 v7, vcc, 0, v7, vcc
	global_load_dwordx4 v[6:9], v[6:7], off
	s_and_saveexec_b64 s[64:65], s[4:5]
	s_cbranch_execz .LBB0_1287
	v_lshl_add_u64 v[10:11], s[48:49], 0, v[58:59]
	v_add_co_u32_e32 v10, vcc, 0x106a2000, v10
	s_nop 1
	v_addc_co_u32_e32 v11, vcc, 0, v11, vcc
	global_load_dwordx4 v[10:13], v[10:11], off

; DI void scan_block(float* ldsf, const u16* __restrict__ R, const u16* __restrict__ KP, const u16* __restrict__ KK, const u16* __restrict__ KKA,
;                    const u16* __restrict__ V, const float* __restrict__ Wd, float* __restrict__ Y, int blk, int wid_k) {
;     ...
;     if (c + 1 < SEQ / 16) SCAN_COMMIT(cur ^ 1);
.LBB0_1290:
	s_or_b64 exec, exec, s[64:65]
	s_andn2_b64 vcc, exec, s[60:61]
	s_cbranch_vccnz .LBB0_1296
	s_cmp_lt_u32 s97, 0x100
	s_cbranch_scc1 .LBB0_1296
	s_lshl_b32 s60, s66, 4
	s_xor_b32 s60, s60, 16
	s_mulk_i32 s60, 0x540
	s_add_i32 s64, s60, 0
	v_lshl_add_u32 v18, v55, 2, s64
	v_add3_u32 v22, v18, v77, v71
	v_add_u32_e32 v89, 0xfffffe00, v22
	s_waitcnt vmcnt(0)
	v_lshlrev_b32_e32 v18, 16, v2
	v_and_b32_e32 v19, 0xffff0000, v2
	v_lshlrev_b32_e32 v20, 16, v3
	v_and_b32_e32 v21, 0xffff0000, v3
	ds_write_b128 v22, v[18:21] offset:256
	v_lshlrev_b32_e32 v18, 16, v4
	v_and_b32_e32 v19, 0xffff0000, v4
	v_lshlrev_b32_e32 v20, 16, v5
	v_and_b32_e32 v21, 0xffff0000, v5
	ds_write_b128 v22, v[18:21] offset:272
	v_lshlrev_b32_e32 v18, 16, v90
	v_and_b32_e32 v19, 0xffff0000, v90
	v_lshlrev_b32_e32 v20, 16, v91
	v_and_b32_e32 v21, 0xffff0000, v91
	ds_write_b128 v89, v[18:21] offset:256
	v_lshlrev_b32_e32 v18, 16, v92
	v_and_b32_e32 v19, 0xffff0000, v92
	v_lshlrev_b32_e32 v20, 16, v93
	v_and_b32_e32 v21, 0xffff0000, v93
	ds_write_b128 v89, v[18:21] offset:272
	v_add3_u32 v18, s64, v72, v54
	ds_write_b128 v18, v[6:9]
	s_and_saveexec_b64 s[60:61], s[4:5]
	s_cbranch_execz .LBB0_1295
	v_add3_u32 v22, s64, v74, v73
	v_lshlrev_b32_e32 v18, 16, v10
	v_and_b32_e32 v19, 0xffff0000, v10
	v_lshlrev_b32_e32 v20, 16, v11
	v_and_b32_e32 v21, 0xffff0000, v11
	ds_write_b128 v22, v[18:21] offset:1280
	v_lshlrev_b32_e32 v18, 16, v12
	v_and_b32_e32 v19, 0xffff0000, v12
	v_lshlrev_b32_e32 v20, 16, v13
	v_and_b32_e32 v21, 0xffff0000, v13
	ds_write_b128 v22, v[18:21] offset:1296
